# BM selected-attention fast path: lane-sum as a 3-level tree interleaved with the fp8 conversions (was a 7-deep dependent chain)
# speedup vs baseline: 1.0230x; 1.0090x over previous
.Lbm2_nostag:
.Lbm2_blkA:
	s_lshl_b32 s12, s15, 12
	s_add_u32 s30, s46, s12
	s_addc_u32 s31, s47, 0
	global_load_dwordx4 v[20:23], v79, s[30:31]
	global_load_dwordx4 v[24:27], v79, s[30:31] offset:1024
	global_load_dwordx4 v[28:31], v79, s[30:31] offset:2048
	global_load_dwordx4 v[32:35], v79, s[30:31] offset:3072
	s_lshl_b32 s12, s15, 12
	s_add_u32 s30, s62, s12
	s_addc_u32 s31, s63, 0
	global_load_dwordx4 v[52:55], v79, s[30:31]
	global_load_dwordx4 v[56:59], v79, s[30:31] offset:1024
	global_load_dwordx4 v[60:63], v79, s[30:31] offset:2048
	global_load_dwordx4 v[64:67], v79, s[30:31] offset:3072
	s_add_i32 s14, s35, 2
	s_add_i32 s13, s25, -1
	s_min_i32 s14, s14, s13
	s_lshl_b32 s13, s14, 2
	s_add_i32 s13, s13, s96
	v_mov_b32_e32 v76, s13
	ds_read_b32 v76, v76 offset:16384
	s_cmp_ge_i32 s54, s21
	s_cselect_b32 s14, 1, 0
	s_bfe_u32 s29, s48, 0x40000
	s_cmp_eq_u32 s29, 0
	s_cbranch_scc1 .Lbm2_Ag0_skip
	s_waitcnt vmcnt(12)
	v_mfma_f32_16x16x32_fp8_fp8 v[84:87], v[2:3], v[164:165], 0
	v_mfma_f32_16x16x32_fp8_fp8 v[88:91], v[6:7], v[164:165], 0
	v_mfma_f32_16x16x32_fp8_fp8 v[92:95], v[12:13], v[164:165], 0
	v_mfma_f32_16x16x32_fp8_fp8 v[96:99], v[16:17], v[164:165], 0
	v_mfma_f32_16x16x32_fp8_fp8 v[84:87], v[4:5], v[166:167], v[84:87]
	v_mfma_f32_16x16x32_fp8_fp8 v[88:91], v[8:9], v[166:167], v[88:91]
	v_mfma_f32_16x16x32_fp8_fp8 v[92:95], v[14:15], v[166:167], v[92:95]
	v_mfma_f32_16x16x32_fp8_fp8 v[96:99], v[18:19], v[166:167], v[96:99]
	v_and_b32_e32 v199, s29, v244
	s_cmp_eq_u32 s14, 1
	v_cmp_ne_u32_e32 vcc, 0, v199
	s_cbranch_scc1 .Lbm2_Ag0_near
	v_add_f32_e32 v200, v81, v190
	v_cndmask_b32_e32 v200, v77, v200, vcc
	v_pk_fma_f32 v[84:85], v[84:85], s[16:17], v[200:201] op_sel_hi:[1,1,0]
	v_pk_fma_f32 v[86:87], v[86:87], s[16:17], v[200:201] op_sel_hi:[1,1,0]
	v_pk_fma_f32 v[88:89], v[88:89], s[16:17], v[200:201] op_sel_hi:[1,1,0]
	v_pk_fma_f32 v[90:91], v[90:91], s[16:17], v[200:201] op_sel_hi:[1,1,0]
	v_pk_fma_f32 v[92:93], v[92:93], s[16:17], v[200:201] op_sel_hi:[1,1,0]
	v_pk_fma_f32 v[94:95], v[94:95], s[16:17], v[200:201] op_sel_hi:[1,1,0]
	v_pk_fma_f32 v[96:97], v[96:97], s[16:17], v[200:201] op_sel_hi:[1,1,0]
	v_pk_fma_f32 v[98:99], v[98:99], s[16:17], v[200:201] op_sel_hi:[1,1,0]
	s_cmp_eq_u32 s35, 0
	s_cbranch_scc1 .Lbm2_Ag0_max
	v_exp_f32_e32 v84, v84
	v_exp_f32_e32 v85, v85
	v_exp_f32_e32 v86, v86
	v_exp_f32_e32 v87, v87
	v_exp_f32_e32 v88, v88
	v_exp_f32_e32 v89, v89
	v_exp_f32_e32 v90, v90
	v_exp_f32_e32 v91, v91
	v_exp_f32_e32 v92, v92
	v_exp_f32_e32 v93, v93
	v_exp_f32_e32 v94, v94
	v_exp_f32_e32 v95, v95
	v_exp_f32_e32 v96, v96
	v_exp_f32_e32 v97, v97
	v_exp_f32_e32 v98, v98
	v_exp_f32_e32 v99, v99
	v_pk_add_f32 v[248:249], v[84:85], v[86:87]
	v_pk_add_f32 v[82:83], v[88:89], v[90:91]
	v_pk_add_f32 v[172:173], v[92:93], v[94:95]
	v_pk_add_f32 v[202:203], v[96:97], v[98:99]
	v_cvt_pk_fp8_f32 v84, v84, v85
	v_cvt_pk_fp8_f32 v85, v88, v89
	v_pk_add_f32 v[248:249], v[248:249], v[82:83]
	v_pk_add_f32 v[172:173], v[172:173], v[202:203]
	v_cvt_pk_fp8_f32 v84, v86, v87 op_sel:[0,0,1]
	v_cvt_pk_fp8_f32 v85, v90, v91 op_sel:[0,0,1]
	v_pk_add_f32 v[248:249], v[248:249], v[172:173]
	v_cvt_pk_fp8_f32 v86, v92, v93
	v_cvt_pk_fp8_f32 v87, v96, v97
	v_add_f32_e32 v248, v248, v249
	v_cvt_pk_fp8_f32 v86, v94, v95 op_sel:[0,0,1]
	v_cvt_pk_fp8_f32 v87, v98, v99 op_sel:[0,0,1]
	v_cmp_lt_f32_e32 vcc, 0x43800000, v248
	s_cbranch_vccnz .Lbm2_Ag0_redo
	v_add_f32_e32 v194, v194, v248
	s_waitcnt vmcnt(8)
	s_nop 1
	v_mfma_f32_16x16x32_fp8_fp8 v[100:103], v[36:37], v[84:85], v[100:103]
	v_mfma_f32_16x16x32_fp8_fp8 v[104:107], v[38:39], v[84:85], v[104:107]
	v_mfma_f32_16x16x32_fp8_fp8 v[108:111], v[40:41], v[84:85], v[108:111]
	v_mfma_f32_16x16x32_fp8_fp8 v[112:115], v[42:43], v[84:85], v[112:115]
	v_mfma_f32_16x16x32_fp8_fp8 v[100:103], v[44:45], v[86:87], v[100:103]
	v_mfma_f32_16x16x32_fp8_fp8 v[104:107], v[46:47], v[86:87], v[104:107]
	v_mfma_f32_16x16x32_fp8_fp8 v[108:111], v[48:49], v[86:87], v[108:111]
	v_mfma_f32_16x16x32_fp8_fp8 v[112:115], v[50:51], v[86:87], v[112:115]
	s_branch .Lbm2_Ag0_skip

.Lbm2_Ag0_skip:
	s_bfe_u32 s29, s48, 0x40004
	s_cmp_eq_u32 s29, 0
	s_cbranch_scc1 .Lbm2_Ag1_skip
	s_waitcnt vmcnt(12)
	v_mfma_f32_16x16x32_fp8_fp8 v[84:87], v[2:3], v[168:169], 0
	v_mfma_f32_16x16x32_fp8_fp8 v[88:91], v[6:7], v[168:169], 0
	v_mfma_f32_16x16x32_fp8_fp8 v[92:95], v[12:13], v[168:169], 0
	v_mfma_f32_16x16x32_fp8_fp8 v[96:99], v[16:17], v[168:169], 0
	v_mfma_f32_16x16x32_fp8_fp8 v[84:87], v[4:5], v[170:171], v[84:87]
	v_mfma_f32_16x16x32_fp8_fp8 v[88:91], v[8:9], v[170:171], v[88:91]
	v_mfma_f32_16x16x32_fp8_fp8 v[92:95], v[14:15], v[170:171], v[92:95]
	v_mfma_f32_16x16x32_fp8_fp8 v[96:99], v[18:19], v[170:171], v[96:99]
	v_and_b32_e32 v199, s29, v244
	s_cmp_eq_u32 s14, 1
	v_cmp_ne_u32_e32 vcc, 0, v199
	s_cbranch_scc1 .Lbm2_Ag1_near
	v_add_f32_e32 v200, v81, v191
	v_cndmask_b32_e32 v200, v77, v200, vcc
	v_pk_fma_f32 v[84:85], v[84:85], s[16:17], v[200:201] op_sel_hi:[1,1,0]
	v_pk_fma_f32 v[86:87], v[86:87], s[16:17], v[200:201] op_sel_hi:[1,1,0]
	v_pk_fma_f32 v[88:89], v[88:89], s[16:17], v[200:201] op_sel_hi:[1,1,0]
	v_pk_fma_f32 v[90:91], v[90:91], s[16:17], v[200:201] op_sel_hi:[1,1,0]
	v_pk_fma_f32 v[92:93], v[92:93], s[16:17], v[200:201] op_sel_hi:[1,1,0]
	v_pk_fma_f32 v[94:95], v[94:95], s[16:17], v[200:201] op_sel_hi:[1,1,0]
	v_pk_fma_f32 v[96:97], v[96:97], s[16:17], v[200:201] op_sel_hi:[1,1,0]
	v_pk_fma_f32 v[98:99], v[98:99], s[16:17], v[200:201] op_sel_hi:[1,1,0]
	s_cmp_eq_u32 s35, 0
	s_cbranch_scc1 .Lbm2_Ag1_max
	v_exp_f32_e32 v84, v84
	v_exp_f32_e32 v85, v85
	v_exp_f32_e32 v86, v86
	v_exp_f32_e32 v87, v87
	v_exp_f32_e32 v88, v88
	v_exp_f32_e32 v89, v89
	v_exp_f32_e32 v90, v90
	v_exp_f32_e32 v91, v91
	v_exp_f32_e32 v92, v92
	v_exp_f32_e32 v93, v93
	v_exp_f32_e32 v94, v94
	v_exp_f32_e32 v95, v95
	v_exp_f32_e32 v96, v96
	v_exp_f32_e32 v97, v97
	v_exp_f32_e32 v98, v98
	v_exp_f32_e32 v99, v99
	v_pk_add_f32 v[248:249], v[84:85], v[86:87]
	v_pk_add_f32 v[82:83], v[88:89], v[90:91]
	v_pk_add_f32 v[172:173], v[92:93], v[94:95]
	v_pk_add_f32 v[202:203], v[96:97], v[98:99]
	v_cvt_pk_fp8_f32 v84, v84, v85
	v_cvt_pk_fp8_f32 v85, v88, v89
	v_pk_add_f32 v[248:249], v[248:249], v[82:83]
	v_pk_add_f32 v[172:173], v[172:173], v[202:203]
	v_cvt_pk_fp8_f32 v84, v86, v87 op_sel:[0,0,1]
	v_cvt_pk_fp8_f32 v85, v90, v91 op_sel:[0,0,1]
	v_pk_add_f32 v[248:249], v[248:249], v[172:173]
	v_cvt_pk_fp8_f32 v86, v92, v93
	v_cvt_pk_fp8_f32 v87, v96, v97
	v_add_f32_e32 v248, v248, v249
	v_cvt_pk_fp8_f32 v86, v94, v95 op_sel:[0,0,1]
	v_cvt_pk_fp8_f32 v87, v98, v99 op_sel:[0,0,1]
	v_cmp_lt_f32_e32 vcc, 0x43800000, v248
	s_cbranch_vccnz .Lbm2_Ag1_redo
	v_add_f32_e32 v195, v195, v248
	s_waitcnt vmcnt(8)
	s_nop 1
	v_mfma_f32_16x16x32_fp8_fp8 v[116:119], v[36:37], v[84:85], v[116:119]
	v_mfma_f32_16x16x32_fp8_fp8 v[120:123], v[38:39], v[84:85], v[120:123]
	v_mfma_f32_16x16x32_fp8_fp8 v[124:127], v[40:41], v[84:85], v[124:127]
	v_mfma_f32_16x16x32_fp8_fp8 v[128:131], v[42:43], v[84:85], v[128:131]
	v_mfma_f32_16x16x32_fp8_fp8 v[116:119], v[44:45], v[86:87], v[116:119]
	v_mfma_f32_16x16x32_fp8_fp8 v[120:123], v[46:47], v[86:87], v[120:123]
	v_mfma_f32_16x16x32_fp8_fp8 v[124:127], v[48:49], v[86:87], v[124:127]
	v_mfma_f32_16x16x32_fp8_fp8 v[128:131], v[50:51], v[86:87], v[128:131]
	s_branch .Lbm2_Ag1_skip

.Lbm2_Ag1_skip:
	s_bfe_u32 s29, s48, 0x40008
	s_cmp_eq_u32 s29, 0
	s_cbranch_scc1 .Lbm2_Ag2_skip
	s_waitcnt vmcnt(12)
	v_mfma_f32_16x16x32_fp8_fp8 v[84:87], v[2:3], v[182:183], 0
	v_mfma_f32_16x16x32_fp8_fp8 v[88:91], v[6:7], v[182:183], 0
	v_mfma_f32_16x16x32_fp8_fp8 v[92:95], v[12:13], v[182:183], 0
	v_mfma_f32_16x16x32_fp8_fp8 v[96:99], v[16:17], v[182:183], 0
	v_mfma_f32_16x16x32_fp8_fp8 v[84:87], v[4:5], v[184:185], v[84:87]
	v_mfma_f32_16x16x32_fp8_fp8 v[88:91], v[8:9], v[184:185], v[88:91]
	v_mfma_f32_16x16x32_fp8_fp8 v[92:95], v[14:15], v[184:185], v[92:95]
	v_mfma_f32_16x16x32_fp8_fp8 v[96:99], v[18:19], v[184:185], v[96:99]
	v_and_b32_e32 v199, s29, v244
	s_cmp_eq_u32 s14, 1
	v_cmp_ne_u32_e32 vcc, 0, v199
	s_cbranch_scc1 .Lbm2_Ag2_near
	v_add_f32_e32 v200, v81, v192
	v_cndmask_b32_e32 v200, v77, v200, vcc
	v_pk_fma_f32 v[84:85], v[84:85], s[16:17], v[200:201] op_sel_hi:[1,1,0]
	v_pk_fma_f32 v[86:87], v[86:87], s[16:17], v[200:201] op_sel_hi:[1,1,0]
	v_pk_fma_f32 v[88:89], v[88:89], s[16:17], v[200:201] op_sel_hi:[1,1,0]
	v_pk_fma_f32 v[90:91], v[90:91], s[16:17], v[200:201] op_sel_hi:[1,1,0]
	v_pk_fma_f32 v[92:93], v[92:93], s[16:17], v[200:201] op_sel_hi:[1,1,0]
	v_pk_fma_f32 v[94:95], v[94:95], s[16:17], v[200:201] op_sel_hi:[1,1,0]
	v_pk_fma_f32 v[96:97], v[96:97], s[16:17], v[200:201] op_sel_hi:[1,1,0]
	v_pk_fma_f32 v[98:99], v[98:99], s[16:17], v[200:201] op_sel_hi:[1,1,0]
	s_cmp_eq_u32 s35, 0
	s_cbranch_scc1 .Lbm2_Ag2_max
	v_exp_f32_e32 v84, v84
	v_exp_f32_e32 v85, v85
	v_exp_f32_e32 v86, v86
	v_exp_f32_e32 v87, v87
	v_exp_f32_e32 v88, v88
	v_exp_f32_e32 v89, v89
	v_exp_f32_e32 v90, v90
	v_exp_f32_e32 v91, v91
	v_exp_f32_e32 v92, v92
	v_exp_f32_e32 v93, v93
	v_exp_f32_e32 v94, v94
	v_exp_f32_e32 v95, v95
	v_exp_f32_e32 v96, v96
	v_exp_f32_e32 v97, v97
	v_exp_f32_e32 v98, v98
	v_exp_f32_e32 v99, v99
	v_pk_add_f32 v[248:249], v[84:85], v[86:87]
	v_pk_add_f32 v[82:83], v[88:89], v[90:91]
	v_pk_add_f32 v[172:173], v[92:93], v[94:95]
	v_pk_add_f32 v[202:203], v[96:97], v[98:99]
	v_cvt_pk_fp8_f32 v84, v84, v85
	v_cvt_pk_fp8_f32 v85, v88, v89
	v_pk_add_f32 v[248:249], v[248:249], v[82:83]
	v_pk_add_f32 v[172:173], v[172:173], v[202:203]
	v_cvt_pk_fp8_f32 v84, v86, v87 op_sel:[0,0,1]
	v_cvt_pk_fp8_f32 v85, v90, v91 op_sel:[0,0,1]
	v_pk_add_f32 v[248:249], v[248:249], v[172:173]
	v_cvt_pk_fp8_f32 v86, v92, v93
	v_cvt_pk_fp8_f32 v87, v96, v97
	v_add_f32_e32 v248, v248, v249
	v_cvt_pk_fp8_f32 v86, v94, v95 op_sel:[0,0,1]
	v_cvt_pk_fp8_f32 v87, v98, v99 op_sel:[0,0,1]
	v_cmp_lt_f32_e32 vcc, 0x43800000, v248
	s_cbranch_vccnz .Lbm2_Ag2_redo
	v_add_f32_e32 v196, v196, v248
	s_waitcnt vmcnt(8)
	s_nop 1
	v_mfma_f32_16x16x32_fp8_fp8 v[132:135], v[36:37], v[84:85], v[132:135]
	v_mfma_f32_16x16x32_fp8_fp8 v[136:139], v[38:39], v[84:85], v[136:139]
	v_mfma_f32_16x16x32_fp8_fp8 v[140:143], v[40:41], v[84:85], v[140:143]
	v_mfma_f32_16x16x32_fp8_fp8 v[144:147], v[42:43], v[84:85], v[144:147]
	v_mfma_f32_16x16x32_fp8_fp8 v[132:135], v[44:45], v[86:87], v[132:135]
	v_mfma_f32_16x16x32_fp8_fp8 v[136:139], v[46:47], v[86:87], v[136:139]
	v_mfma_f32_16x16x32_fp8_fp8 v[140:143], v[48:49], v[86:87], v[140:143]
	v_mfma_f32_16x16x32_fp8_fp8 v[144:147], v[50:51], v[86:87], v[144:147]
	s_branch .Lbm2_Ag2_skip

.Lbm2_Ag2_skip:
	s_bfe_u32 s29, s48, 0x4000c
	s_cmp_eq_u32 s29, 0
	s_cbranch_scc1 .Lbm2_Ag3_skip
	s_waitcnt vmcnt(12)
	v_mfma_f32_16x16x32_fp8_fp8 v[84:87], v[2:3], v[186:187], 0
	v_mfma_f32_16x16x32_fp8_fp8 v[88:91], v[6:7], v[186:187], 0
	v_mfma_f32_16x16x32_fp8_fp8 v[92:95], v[12:13], v[186:187], 0
	v_mfma_f32_16x16x32_fp8_fp8 v[96:99], v[16:17], v[186:187], 0
	v_mfma_f32_16x16x32_fp8_fp8 v[84:87], v[4:5], v[188:189], v[84:87]
	v_mfma_f32_16x16x32_fp8_fp8 v[88:91], v[8:9], v[188:189], v[88:91]
	v_mfma_f32_16x16x32_fp8_fp8 v[92:95], v[14:15], v[188:189], v[92:95]
	v_mfma_f32_16x16x32_fp8_fp8 v[96:99], v[18:19], v[188:189], v[96:99]
	v_and_b32_e32 v199, s29, v244
	s_cmp_eq_u32 s14, 1
	v_cmp_ne_u32_e32 vcc, 0, v199
	s_cbranch_scc1 .Lbm2_Ag3_near
	v_add_f32_e32 v200, v81, v193
	v_cndmask_b32_e32 v200, v77, v200, vcc
	v_pk_fma_f32 v[84:85], v[84:85], s[16:17], v[200:201] op_sel_hi:[1,1,0]
	v_pk_fma_f32 v[86:87], v[86:87], s[16:17], v[200:201] op_sel_hi:[1,1,0]
	v_pk_fma_f32 v[88:89], v[88:89], s[16:17], v[200:201] op_sel_hi:[1,1,0]
	v_pk_fma_f32 v[90:91], v[90:91], s[16:17], v[200:201] op_sel_hi:[1,1,0]
	v_pk_fma_f32 v[92:93], v[92:93], s[16:17], v[200:201] op_sel_hi:[1,1,0]
	v_pk_fma_f32 v[94:95], v[94:95], s[16:17], v[200:201] op_sel_hi:[1,1,0]
	v_pk_fma_f32 v[96:97], v[96:97], s[16:17], v[200:201] op_sel_hi:[1,1,0]
	v_pk_fma_f32 v[98:99], v[98:99], s[16:17], v[200:201] op_sel_hi:[1,1,0]
	s_cmp_eq_u32 s35, 0
	s_cbranch_scc1 .Lbm2_Ag3_max
	v_exp_f32_e32 v84, v84
	v_exp_f32_e32 v85, v85
	v_exp_f32_e32 v86, v86
	v_exp_f32_e32 v87, v87
	v_exp_f32_e32 v88, v88
	v_exp_f32_e32 v89, v89
	v_exp_f32_e32 v90, v90
	v_exp_f32_e32 v91, v91
	v_exp_f32_e32 v92, v92
	v_exp_f32_e32 v93, v93
	v_exp_f32_e32 v94, v94
	v_exp_f32_e32 v95, v95
	v_exp_f32_e32 v96, v96
	v_exp_f32_e32 v97, v97
	v_exp_f32_e32 v98, v98
	v_exp_f32_e32 v99, v99
	v_pk_add_f32 v[248:249], v[84:85], v[86:87]
	v_pk_add_f32 v[82:83], v[88:89], v[90:91]
	v_pk_add_f32 v[172:173], v[92:93], v[94:95]
	v_pk_add_f32 v[202:203], v[96:97], v[98:99]
	v_cvt_pk_fp8_f32 v84, v84, v85
	v_cvt_pk_fp8_f32 v85, v88, v89
	v_pk_add_f32 v[248:249], v[248:249], v[82:83]
	v_pk_add_f32 v[172:173], v[172:173], v[202:203]
	v_cvt_pk_fp8_f32 v84, v86, v87 op_sel:[0,0,1]
	v_cvt_pk_fp8_f32 v85, v90, v91 op_sel:[0,0,1]
	v_pk_add_f32 v[248:249], v[248:249], v[172:173]
	v_cvt_pk_fp8_f32 v86, v92, v93
	v_cvt_pk_fp8_f32 v87, v96, v97
	v_add_f32_e32 v248, v248, v249
	v_cvt_pk_fp8_f32 v86, v94, v95 op_sel:[0,0,1]
	v_cvt_pk_fp8_f32 v87, v98, v99 op_sel:[0,0,1]
	v_cmp_lt_f32_e32 vcc, 0x43800000, v248
	s_cbranch_vccnz .Lbm2_Ag3_redo
	v_add_f32_e32 v197, v197, v248
	s_waitcnt vmcnt(8)
	s_nop 1
	v_mfma_f32_16x16x32_fp8_fp8 v[148:151], v[36:37], v[84:85], v[148:151]
	v_mfma_f32_16x16x32_fp8_fp8 v[152:155], v[38:39], v[84:85], v[152:155]
	v_mfma_f32_16x16x32_fp8_fp8 v[156:159], v[40:41], v[84:85], v[156:159]
	v_mfma_f32_16x16x32_fp8_fp8 v[160:163], v[42:43], v[84:85], v[160:163]
	v_mfma_f32_16x16x32_fp8_fp8 v[148:151], v[44:45], v[86:87], v[148:151]
	v_mfma_f32_16x16x32_fp8_fp8 v[152:155], v[46:47], v[86:87], v[152:155]
	v_mfma_f32_16x16x32_fp8_fp8 v[156:159], v[48:49], v[86:87], v[156:159]
	v_mfma_f32_16x16x32_fp8_fp8 v[160:163], v[50:51], v[86:87], v[160:163]
	s_branch .Lbm2_Ag3_skip

.Lbm2_blkB:
	s_lshl_b32 s12, s15, 12
	s_add_u32 s30, s46, s12
	s_addc_u32 s31, s47, 0
	global_load_dwordx4 v[2:5], v79, s[30:31]
	global_load_dwordx4 v[6:9], v79, s[30:31] offset:1024
	global_load_dwordx4 v[12:15], v79, s[30:31] offset:2048
	global_load_dwordx4 v[16:19], v79, s[30:31] offset:3072
	s_lshl_b32 s12, s15, 12
	s_add_u32 s30, s62, s12
	s_addc_u32 s31, s63, 0
	global_load_dwordx4 v[36:39], v79, s[30:31]
	global_load_dwordx4 v[40:43], v79, s[30:31] offset:1024
	global_load_dwordx4 v[44:47], v79, s[30:31] offset:2048
	global_load_dwordx4 v[48:51], v79, s[30:31] offset:3072
	s_add_i32 s14, s35, 2
	s_add_i32 s13, s25, -1
	s_min_i32 s14, s14, s13
	s_lshl_b32 s13, s14, 2
	s_add_i32 s13, s13, s96
	v_mov_b32_e32 v76, s13
	ds_read_b32 v76, v76 offset:16384
	s_cmp_ge_i32 s54, s21
	s_cselect_b32 s14, 1, 0
	s_bfe_u32 s29, s48, 0x40000
	s_cmp_eq_u32 s29, 0
	s_cbranch_scc1 .Lbm2_Bg0_skip
	s_waitcnt vmcnt(12)
	v_mfma_f32_16x16x32_fp8_fp8 v[84:87], v[20:21], v[164:165], 0
	v_mfma_f32_16x16x32_fp8_fp8 v[88:91], v[24:25], v[164:165], 0
	v_mfma_f32_16x16x32_fp8_fp8 v[92:95], v[28:29], v[164:165], 0
	v_mfma_f32_16x16x32_fp8_fp8 v[96:99], v[32:33], v[164:165], 0
	v_mfma_f32_16x16x32_fp8_fp8 v[84:87], v[22:23], v[166:167], v[84:87]
	v_mfma_f32_16x16x32_fp8_fp8 v[88:91], v[26:27], v[166:167], v[88:91]
	v_mfma_f32_16x16x32_fp8_fp8 v[92:95], v[30:31], v[166:167], v[92:95]
	v_mfma_f32_16x16x32_fp8_fp8 v[96:99], v[34:35], v[166:167], v[96:99]
	v_and_b32_e32 v199, s29, v244
	s_cmp_eq_u32 s14, 1
	v_cmp_ne_u32_e32 vcc, 0, v199
	s_cbranch_scc1 .Lbm2_Bg0_near
	v_add_f32_e32 v200, v81, v190
	v_cndmask_b32_e32 v200, v77, v200, vcc
	v_pk_fma_f32 v[84:85], v[84:85], s[16:17], v[200:201] op_sel_hi:[1,1,0]
	v_pk_fma_f32 v[86:87], v[86:87], s[16:17], v[200:201] op_sel_hi:[1,1,0]
	v_pk_fma_f32 v[88:89], v[88:89], s[16:17], v[200:201] op_sel_hi:[1,1,0]
	v_pk_fma_f32 v[90:91], v[90:91], s[16:17], v[200:201] op_sel_hi:[1,1,0]
	v_pk_fma_f32 v[92:93], v[92:93], s[16:17], v[200:201] op_sel_hi:[1,1,0]
	v_pk_fma_f32 v[94:95], v[94:95], s[16:17], v[200:201] op_sel_hi:[1,1,0]
	v_pk_fma_f32 v[96:97], v[96:97], s[16:17], v[200:201] op_sel_hi:[1,1,0]
	v_pk_fma_f32 v[98:99], v[98:99], s[16:17], v[200:201] op_sel_hi:[1,1,0]
	s_cmp_eq_u32 s35, 0
	s_cbranch_scc1 .Lbm2_Bg0_max
	v_exp_f32_e32 v84, v84
	v_exp_f32_e32 v85, v85
	v_exp_f32_e32 v86, v86
	v_exp_f32_e32 v87, v87
	v_exp_f32_e32 v88, v88
	v_exp_f32_e32 v89, v89
	v_exp_f32_e32 v90, v90
	v_exp_f32_e32 v91, v91
	v_exp_f32_e32 v92, v92
	v_exp_f32_e32 v93, v93
	v_exp_f32_e32 v94, v94
	v_exp_f32_e32 v95, v95
	v_exp_f32_e32 v96, v96
	v_exp_f32_e32 v97, v97
	v_exp_f32_e32 v98, v98
	v_exp_f32_e32 v99, v99
	v_pk_add_f32 v[248:249], v[84:85], v[86:87]
	v_pk_add_f32 v[82:83], v[88:89], v[90:91]
	v_pk_add_f32 v[172:173], v[92:93], v[94:95]
	v_pk_add_f32 v[202:203], v[96:97], v[98:99]
	v_cvt_pk_fp8_f32 v84, v84, v85
	v_cvt_pk_fp8_f32 v85, v88, v89
	v_pk_add_f32 v[248:249], v[248:249], v[82:83]
	v_pk_add_f32 v[172:173], v[172:173], v[202:203]
	v_cvt_pk_fp8_f32 v84, v86, v87 op_sel:[0,0,1]
	v_cvt_pk_fp8_f32 v85, v90, v91 op_sel:[0,0,1]
	v_pk_add_f32 v[248:249], v[248:249], v[172:173]
	v_cvt_pk_fp8_f32 v86, v92, v93
	v_cvt_pk_fp8_f32 v87, v96, v97
	v_add_f32_e32 v248, v248, v249
	v_cvt_pk_fp8_f32 v86, v94, v95 op_sel:[0,0,1]
	v_cvt_pk_fp8_f32 v87, v98, v99 op_sel:[0,0,1]
	v_cmp_lt_f32_e32 vcc, 0x43800000, v248
	s_cbranch_vccnz .Lbm2_Bg0_redo
	v_add_f32_e32 v194, v194, v248
	s_waitcnt vmcnt(8)
	s_nop 1
	v_mfma_f32_16x16x32_fp8_fp8 v[100:103], v[52:53], v[84:85], v[100:103]
	v_mfma_f32_16x16x32_fp8_fp8 v[104:107], v[54:55], v[84:85], v[104:107]
	v_mfma_f32_16x16x32_fp8_fp8 v[108:111], v[56:57], v[84:85], v[108:111]
	v_mfma_f32_16x16x32_fp8_fp8 v[112:115], v[58:59], v[84:85], v[112:115]
	v_mfma_f32_16x16x32_fp8_fp8 v[100:103], v[60:61], v[86:87], v[100:103]
	v_mfma_f32_16x16x32_fp8_fp8 v[104:107], v[62:63], v[86:87], v[104:107]
	v_mfma_f32_16x16x32_fp8_fp8 v[108:111], v[64:65], v[86:87], v[108:111]
	v_mfma_f32_16x16x32_fp8_fp8 v[112:115], v[66:67], v[86:87], v[112:115]
	s_branch .Lbm2_Bg0_skip

.Lbm2_Bg0_skip:
	s_bfe_u32 s29, s48, 0x40004
	s_cmp_eq_u32 s29, 0
	s_cbranch_scc1 .Lbm2_Bg1_skip
	s_waitcnt vmcnt(12)
	v_mfma_f32_16x16x32_fp8_fp8 v[84:87], v[20:21], v[168:169], 0
	v_mfma_f32_16x16x32_fp8_fp8 v[88:91], v[24:25], v[168:169], 0
	v_mfma_f32_16x16x32_fp8_fp8 v[92:95], v[28:29], v[168:169], 0
	v_mfma_f32_16x16x32_fp8_fp8 v[96:99], v[32:33], v[168:169], 0
	v_mfma_f32_16x16x32_fp8_fp8 v[84:87], v[22:23], v[170:171], v[84:87]
	v_mfma_f32_16x16x32_fp8_fp8 v[88:91], v[26:27], v[170:171], v[88:91]
	v_mfma_f32_16x16x32_fp8_fp8 v[92:95], v[30:31], v[170:171], v[92:95]
	v_mfma_f32_16x16x32_fp8_fp8 v[96:99], v[34:35], v[170:171], v[96:99]
	v_and_b32_e32 v199, s29, v244
	s_cmp_eq_u32 s14, 1
	v_cmp_ne_u32_e32 vcc, 0, v199
	s_cbranch_scc1 .Lbm2_Bg1_near
	v_add_f32_e32 v200, v81, v191
	v_cndmask_b32_e32 v200, v77, v200, vcc
	v_pk_fma_f32 v[84:85], v[84:85], s[16:17], v[200:201] op_sel_hi:[1,1,0]
	v_pk_fma_f32 v[86:87], v[86:87], s[16:17], v[200:201] op_sel_hi:[1,1,0]
	v_pk_fma_f32 v[88:89], v[88:89], s[16:17], v[200:201] op_sel_hi:[1,1,0]
	v_pk_fma_f32 v[90:91], v[90:91], s[16:17], v[200:201] op_sel_hi:[1,1,0]
	v_pk_fma_f32 v[92:93], v[92:93], s[16:17], v[200:201] op_sel_hi:[1,1,0]
	v_pk_fma_f32 v[94:95], v[94:95], s[16:17], v[200:201] op_sel_hi:[1,1,0]
	v_pk_fma_f32 v[96:97], v[96:97], s[16:17], v[200:201] op_sel_hi:[1,1,0]
	v_pk_fma_f32 v[98:99], v[98:99], s[16:17], v[200:201] op_sel_hi:[1,1,0]
	s_cmp_eq_u32 s35, 0
	s_cbranch_scc1 .Lbm2_Bg1_max
	v_exp_f32_e32 v84, v84
	v_exp_f32_e32 v85, v85
	v_exp_f32_e32 v86, v86
	v_exp_f32_e32 v87, v87
	v_exp_f32_e32 v88, v88
	v_exp_f32_e32 v89, v89
	v_exp_f32_e32 v90, v90
	v_exp_f32_e32 v91, v91
	v_exp_f32_e32 v92, v92
	v_exp_f32_e32 v93, v93
	v_exp_f32_e32 v94, v94
	v_exp_f32_e32 v95, v95
	v_exp_f32_e32 v96, v96
	v_exp_f32_e32 v97, v97
	v_exp_f32_e32 v98, v98
	v_exp_f32_e32 v99, v99
	v_pk_add_f32 v[248:249], v[84:85], v[86:87]
	v_pk_add_f32 v[82:83], v[88:89], v[90:91]
	v_pk_add_f32 v[172:173], v[92:93], v[94:95]
	v_pk_add_f32 v[202:203], v[96:97], v[98:99]
	v_cvt_pk_fp8_f32 v84, v84, v85
	v_cvt_pk_fp8_f32 v85, v88, v89
	v_pk_add_f32 v[248:249], v[248:249], v[82:83]
	v_pk_add_f32 v[172:173], v[172:173], v[202:203]
	v_cvt_pk_fp8_f32 v84, v86, v87 op_sel:[0,0,1]
	v_cvt_pk_fp8_f32 v85, v90, v91 op_sel:[0,0,1]
	v_pk_add_f32 v[248:249], v[248:249], v[172:173]
	v_cvt_pk_fp8_f32 v86, v92, v93
	v_cvt_pk_fp8_f32 v87, v96, v97
	v_add_f32_e32 v248, v248, v249
	v_cvt_pk_fp8_f32 v86, v94, v95 op_sel:[0,0,1]
	v_cvt_pk_fp8_f32 v87, v98, v99 op_sel:[0,0,1]
	v_cmp_lt_f32_e32 vcc, 0x43800000, v248
	s_cbranch_vccnz .Lbm2_Bg1_redo
	v_add_f32_e32 v195, v195, v248
	s_waitcnt vmcnt(8)
	s_nop 1
	v_mfma_f32_16x16x32_fp8_fp8 v[116:119], v[52:53], v[84:85], v[116:119]
	v_mfma_f32_16x16x32_fp8_fp8 v[120:123], v[54:55], v[84:85], v[120:123]
	v_mfma_f32_16x16x32_fp8_fp8 v[124:127], v[56:57], v[84:85], v[124:127]
	v_mfma_f32_16x16x32_fp8_fp8 v[128:131], v[58:59], v[84:85], v[128:131]
	v_mfma_f32_16x16x32_fp8_fp8 v[116:119], v[60:61], v[86:87], v[116:119]
	v_mfma_f32_16x16x32_fp8_fp8 v[120:123], v[62:63], v[86:87], v[120:123]
	v_mfma_f32_16x16x32_fp8_fp8 v[124:127], v[64:65], v[86:87], v[124:127]
	v_mfma_f32_16x16x32_fp8_fp8 v[128:131], v[66:67], v[86:87], v[128:131]
	s_branch .Lbm2_Bg1_skip

.Lbm2_Bg1_skip:
	s_bfe_u32 s29, s48, 0x40008
	s_cmp_eq_u32 s29, 0
	s_cbranch_scc1 .Lbm2_Bg2_skip
	s_waitcnt vmcnt(12)
	v_mfma_f32_16x16x32_fp8_fp8 v[84:87], v[20:21], v[182:183], 0
	v_mfma_f32_16x16x32_fp8_fp8 v[88:91], v[24:25], v[182:183], 0
	v_mfma_f32_16x16x32_fp8_fp8 v[92:95], v[28:29], v[182:183], 0
	v_mfma_f32_16x16x32_fp8_fp8 v[96:99], v[32:33], v[182:183], 0
	v_mfma_f32_16x16x32_fp8_fp8 v[84:87], v[22:23], v[184:185], v[84:87]
	v_mfma_f32_16x16x32_fp8_fp8 v[88:91], v[26:27], v[184:185], v[88:91]
	v_mfma_f32_16x16x32_fp8_fp8 v[92:95], v[30:31], v[184:185], v[92:95]
	v_mfma_f32_16x16x32_fp8_fp8 v[96:99], v[34:35], v[184:185], v[96:99]
	v_and_b32_e32 v199, s29, v244
	s_cmp_eq_u32 s14, 1
	v_cmp_ne_u32_e32 vcc, 0, v199
	s_cbranch_scc1 .Lbm2_Bg2_near
	v_add_f32_e32 v200, v81, v192
	v_cndmask_b32_e32 v200, v77, v200, vcc
	v_pk_fma_f32 v[84:85], v[84:85], s[16:17], v[200:201] op_sel_hi:[1,1,0]
	v_pk_fma_f32 v[86:87], v[86:87], s[16:17], v[200:201] op_sel_hi:[1,1,0]
	v_pk_fma_f32 v[88:89], v[88:89], s[16:17], v[200:201] op_sel_hi:[1,1,0]
	v_pk_fma_f32 v[90:91], v[90:91], s[16:17], v[200:201] op_sel_hi:[1,1,0]
	v_pk_fma_f32 v[92:93], v[92:93], s[16:17], v[200:201] op_sel_hi:[1,1,0]
	v_pk_fma_f32 v[94:95], v[94:95], s[16:17], v[200:201] op_sel_hi:[1,1,0]
	v_pk_fma_f32 v[96:97], v[96:97], s[16:17], v[200:201] op_sel_hi:[1,1,0]
	v_pk_fma_f32 v[98:99], v[98:99], s[16:17], v[200:201] op_sel_hi:[1,1,0]
	s_cmp_eq_u32 s35, 0
	s_cbranch_scc1 .Lbm2_Bg2_max
	v_exp_f32_e32 v84, v84
	v_exp_f32_e32 v85, v85
	v_exp_f32_e32 v86, v86
	v_exp_f32_e32 v87, v87
	v_exp_f32_e32 v88, v88
	v_exp_f32_e32 v89, v89
	v_exp_f32_e32 v90, v90
	v_exp_f32_e32 v91, v91
	v_exp_f32_e32 v92, v92
	v_exp_f32_e32 v93, v93
	v_exp_f32_e32 v94, v94
	v_exp_f32_e32 v95, v95
	v_exp_f32_e32 v96, v96
	v_exp_f32_e32 v97, v97
	v_exp_f32_e32 v98, v98
	v_exp_f32_e32 v99, v99
	v_pk_add_f32 v[248:249], v[84:85], v[86:87]
	v_pk_add_f32 v[82:83], v[88:89], v[90:91]
	v_pk_add_f32 v[172:173], v[92:93], v[94:95]
	v_pk_add_f32 v[202:203], v[96:97], v[98:99]
	v_cvt_pk_fp8_f32 v84, v84, v85
	v_cvt_pk_fp8_f32 v85, v88, v89
	v_pk_add_f32 v[248:249], v[248:249], v[82:83]
	v_pk_add_f32 v[172:173], v[172:173], v[202:203]
	v_cvt_pk_fp8_f32 v84, v86, v87 op_sel:[0,0,1]
	v_cvt_pk_fp8_f32 v85, v90, v91 op_sel:[0,0,1]
	v_pk_add_f32 v[248:249], v[248:249], v[172:173]
	v_cvt_pk_fp8_f32 v86, v92, v93
	v_cvt_pk_fp8_f32 v87, v96, v97
	v_add_f32_e32 v248, v248, v249
	v_cvt_pk_fp8_f32 v86, v94, v95 op_sel:[0,0,1]
	v_cvt_pk_fp8_f32 v87, v98, v99 op_sel:[0,0,1]
	v_cmp_lt_f32_e32 vcc, 0x43800000, v248
	s_cbranch_vccnz .Lbm2_Bg2_redo
	v_add_f32_e32 v196, v196, v248
	s_waitcnt vmcnt(8)
	s_nop 1
	v_mfma_f32_16x16x32_fp8_fp8 v[132:135], v[52:53], v[84:85], v[132:135]
	v_mfma_f32_16x16x32_fp8_fp8 v[136:139], v[54:55], v[84:85], v[136:139]
	v_mfma_f32_16x16x32_fp8_fp8 v[140:143], v[56:57], v[84:85], v[140:143]
	v_mfma_f32_16x16x32_fp8_fp8 v[144:147], v[58:59], v[84:85], v[144:147]
	v_mfma_f32_16x16x32_fp8_fp8 v[132:135], v[60:61], v[86:87], v[132:135]
	v_mfma_f32_16x16x32_fp8_fp8 v[136:139], v[62:63], v[86:87], v[136:139]
	v_mfma_f32_16x16x32_fp8_fp8 v[140:143], v[64:65], v[86:87], v[140:143]
	v_mfma_f32_16x16x32_fp8_fp8 v[144:147], v[66:67], v[86:87], v[144:147]
	s_branch .Lbm2_Bg2_skip

.Lbm2_Bg2_skip:
	s_bfe_u32 s29, s48, 0x4000c
	s_cmp_eq_u32 s29, 0
	s_cbranch_scc1 .Lbm2_Bg3_skip
	s_waitcnt vmcnt(12)
	v_mfma_f32_16x16x32_fp8_fp8 v[84:87], v[20:21], v[186:187], 0
	v_mfma_f32_16x16x32_fp8_fp8 v[88:91], v[24:25], v[186:187], 0
	v_mfma_f32_16x16x32_fp8_fp8 v[92:95], v[28:29], v[186:187], 0
	v_mfma_f32_16x16x32_fp8_fp8 v[96:99], v[32:33], v[186:187], 0
	v_mfma_f32_16x16x32_fp8_fp8 v[84:87], v[22:23], v[188:189], v[84:87]
	v_mfma_f32_16x16x32_fp8_fp8 v[88:91], v[26:27], v[188:189], v[88:91]
	v_mfma_f32_16x16x32_fp8_fp8 v[92:95], v[30:31], v[188:189], v[92:95]
	v_mfma_f32_16x16x32_fp8_fp8 v[96:99], v[34:35], v[188:189], v[96:99]
	v_and_b32_e32 v199, s29, v244
	s_cmp_eq_u32 s14, 1
	v_cmp_ne_u32_e32 vcc, 0, v199
	s_cbranch_scc1 .Lbm2_Bg3_near
	v_add_f32_e32 v200, v81, v193
	v_cndmask_b32_e32 v200, v77, v200, vcc
	v_pk_fma_f32 v[84:85], v[84:85], s[16:17], v[200:201] op_sel_hi:[1,1,0]
	v_pk_fma_f32 v[86:87], v[86:87], s[16:17], v[200:201] op_sel_hi:[1,1,0]
	v_pk_fma_f32 v[88:89], v[88:89], s[16:17], v[200:201] op_sel_hi:[1,1,0]
	v_pk_fma_f32 v[90:91], v[90:91], s[16:17], v[200:201] op_sel_hi:[1,1,0]
	v_pk_fma_f32 v[92:93], v[92:93], s[16:17], v[200:201] op_sel_hi:[1,1,0]
	v_pk_fma_f32 v[94:95], v[94:95], s[16:17], v[200:201] op_sel_hi:[1,1,0]
	v_pk_fma_f32 v[96:97], v[96:97], s[16:17], v[200:201] op_sel_hi:[1,1,0]
	v_pk_fma_f32 v[98:99], v[98:99], s[16:17], v[200:201] op_sel_hi:[1,1,0]
	s_cmp_eq_u32 s35, 0
	s_cbranch_scc1 .Lbm2_Bg3_max
	v_exp_f32_e32 v84, v84
	v_exp_f32_e32 v85, v85
	v_exp_f32_e32 v86, v86
	v_exp_f32_e32 v87, v87
	v_exp_f32_e32 v88, v88
	v_exp_f32_e32 v89, v89
	v_exp_f32_e32 v90, v90
	v_exp_f32_e32 v91, v91
	v_exp_f32_e32 v92, v92
	v_exp_f32_e32 v93, v93
	v_exp_f32_e32 v94, v94
	v_exp_f32_e32 v95, v95
	v_exp_f32_e32 v96, v96
	v_exp_f32_e32 v97, v97
	v_exp_f32_e32 v98, v98
	v_exp_f32_e32 v99, v99
	v_pk_add_f32 v[248:249], v[84:85], v[86:87]
	v_pk_add_f32 v[82:83], v[88:89], v[90:91]
	v_pk_add_f32 v[172:173], v[92:93], v[94:95]
	v_pk_add_f32 v[202:203], v[96:97], v[98:99]
	v_cvt_pk_fp8_f32 v84, v84, v85
	v_cvt_pk_fp8_f32 v85, v88, v89
	v_pk_add_f32 v[248:249], v[248:249], v[82:83]
	v_pk_add_f32 v[172:173], v[172:173], v[202:203]
	v_cvt_pk_fp8_f32 v84, v86, v87 op_sel:[0,0,1]
	v_cvt_pk_fp8_f32 v85, v90, v91 op_sel:[0,0,1]
	v_pk_add_f32 v[248:249], v[248:249], v[172:173]
	v_cvt_pk_fp8_f32 v86, v92, v93
	v_cvt_pk_fp8_f32 v87, v96, v97
	v_add_f32_e32 v248, v248, v249
	v_cvt_pk_fp8_f32 v86, v94, v95 op_sel:[0,0,1]
	v_cvt_pk_fp8_f32 v87, v98, v99 op_sel:[0,0,1]
	v_cmp_lt_f32_e32 vcc, 0x43800000, v248
	s_cbranch_vccnz .Lbm2_Bg3_redo
	v_add_f32_e32 v197, v197, v248
	s_waitcnt vmcnt(8)
	s_nop 1
	v_mfma_f32_16x16x32_fp8_fp8 v[148:151], v[52:53], v[84:85], v[148:151]
	v_mfma_f32_16x16x32_fp8_fp8 v[152:155], v[54:55], v[84:85], v[152:155]
	v_mfma_f32_16x16x32_fp8_fp8 v[156:159], v[56:57], v[84:85], v[156:159]
	v_mfma_f32_16x16x32_fp8_fp8 v[160:163], v[58:59], v[84:85], v[160:163]
	v_mfma_f32_16x16x32_fp8_fp8 v[148:151], v[60:61], v[86:87], v[148:151]
	v_mfma_f32_16x16x32_fp8_fp8 v[152:155], v[62:63], v[86:87], v[152:155]
	v_mfma_f32_16x16x32_fp8_fp8 v[156:159], v[64:65], v[86:87], v[156:159]
	v_mfma_f32_16x16x32_fp8_fp8 v[160:163], v[66:67], v[86:87], v[160:163]
	s_branch .Lbm2_Bg3_skip

.Lbm3_nostag:
.Lbm3_blkA:
	s_lshl_b32 s29, s27, 12
	s_add_u32 s30, s40, s29
	s_addc_u32 s31, s41, 0
	global_load_dwordx4 v[20:23], v79, s[30:31]
	global_load_dwordx4 v[24:27], v79, s[30:31] offset:1024
	global_load_dwordx4 v[28:31], v79, s[30:31] offset:2048
	global_load_dwordx4 v[32:35], v79, s[30:31] offset:3072
	s_lshl_b32 s29, s27, 12
	s_add_u32 s30, s62, s29
	s_addc_u32 s31, s63, 0
	global_load_dwordx4 v[52:55], v79, s[30:31]
	global_load_dwordx4 v[56:59], v79, s[30:31] offset:1024
	global_load_dwordx4 v[60:63], v79, s[30:31] offset:2048
	global_load_dwordx4 v[64:67], v79, s[30:31] offset:3072
	s_add_i32 s50, s35, 2
	s_add_i32 s9, s25, -1
	s_min_i32 s50, s50, s9
	s_lshl_b32 s9, s50, 2
	s_add_i32 s9, s9, s46
	v_mov_b32_e32 v76, s9
	ds_read_b32 v76, v76 offset:16384
	s_cmp_ge_i32 s38, s21
	s_cselect_b32 s50, 1, 0
	s_bfe_u32 s29, s48, 0x40000
	s_cmp_eq_u32 s29, 0
	s_cbranch_scc1 .Lbm3_Ag0_skip
	s_waitcnt vmcnt(12)
	v_mfma_f32_16x16x32_fp8_fp8 v[84:87], v[2:3], v[164:165], 0
	v_mfma_f32_16x16x32_fp8_fp8 v[88:91], v[6:7], v[164:165], 0
	v_mfma_f32_16x16x32_fp8_fp8 v[92:95], v[12:13], v[164:165], 0
	v_mfma_f32_16x16x32_fp8_fp8 v[96:99], v[16:17], v[164:165], 0
	v_mfma_f32_16x16x32_fp8_fp8 v[84:87], v[4:5], v[166:167], v[84:87]
	v_mfma_f32_16x16x32_fp8_fp8 v[88:91], v[8:9], v[166:167], v[88:91]
	v_mfma_f32_16x16x32_fp8_fp8 v[92:95], v[14:15], v[166:167], v[92:95]
	v_mfma_f32_16x16x32_fp8_fp8 v[96:99], v[18:19], v[166:167], v[96:99]
	v_and_b32_e32 v199, s29, v244
	s_cmp_eq_u32 s50, 1
	v_cmp_ne_u32_e32 vcc, 0, v199
	s_cbranch_scc1 .Lbm3_Ag0_near
	v_add_f32_e32 v200, v81, v190
	v_cndmask_b32_e32 v200, v77, v200, vcc
	v_pk_fma_f32 v[84:85], v[84:85], s[10:11], v[200:201] op_sel_hi:[1,1,0]
	v_pk_fma_f32 v[86:87], v[86:87], s[10:11], v[200:201] op_sel_hi:[1,1,0]
	v_pk_fma_f32 v[88:89], v[88:89], s[10:11], v[200:201] op_sel_hi:[1,1,0]
	v_pk_fma_f32 v[90:91], v[90:91], s[10:11], v[200:201] op_sel_hi:[1,1,0]
	v_pk_fma_f32 v[92:93], v[92:93], s[10:11], v[200:201] op_sel_hi:[1,1,0]
	v_pk_fma_f32 v[94:95], v[94:95], s[10:11], v[200:201] op_sel_hi:[1,1,0]
	v_pk_fma_f32 v[96:97], v[96:97], s[10:11], v[200:201] op_sel_hi:[1,1,0]
	v_pk_fma_f32 v[98:99], v[98:99], s[10:11], v[200:201] op_sel_hi:[1,1,0]
	s_cmp_eq_u32 s35, 0
	s_cbranch_scc1 .Lbm3_Ag0_max
	v_exp_f32_e32 v84, v84
	v_exp_f32_e32 v85, v85
	v_exp_f32_e32 v86, v86
	v_exp_f32_e32 v87, v87
	v_exp_f32_e32 v88, v88
	v_exp_f32_e32 v89, v89
	v_exp_f32_e32 v90, v90
	v_exp_f32_e32 v91, v91
	v_exp_f32_e32 v92, v92
	v_exp_f32_e32 v93, v93
	v_exp_f32_e32 v94, v94
	v_exp_f32_e32 v95, v95
	v_exp_f32_e32 v96, v96
	v_exp_f32_e32 v97, v97
	v_exp_f32_e32 v98, v98
	v_exp_f32_e32 v99, v99
	v_pk_add_f32 v[248:249], v[84:85], v[86:87]
	v_pk_add_f32 v[82:83], v[88:89], v[90:91]
	v_pk_add_f32 v[172:173], v[92:93], v[94:95]
	v_pk_add_f32 v[202:203], v[96:97], v[98:99]
	v_cvt_pk_fp8_f32 v84, v84, v85
	v_cvt_pk_fp8_f32 v85, v88, v89
	v_pk_add_f32 v[248:249], v[248:249], v[82:83]
	v_pk_add_f32 v[172:173], v[172:173], v[202:203]
	v_cvt_pk_fp8_f32 v84, v86, v87 op_sel:[0,0,1]
	v_cvt_pk_fp8_f32 v85, v90, v91 op_sel:[0,0,1]
	v_pk_add_f32 v[248:249], v[248:249], v[172:173]
	v_cvt_pk_fp8_f32 v86, v92, v93
	v_cvt_pk_fp8_f32 v87, v96, v97
	v_add_f32_e32 v248, v248, v249
	v_cvt_pk_fp8_f32 v86, v94, v95 op_sel:[0,0,1]
	v_cvt_pk_fp8_f32 v87, v98, v99 op_sel:[0,0,1]
	v_cmp_lt_f32_e32 vcc, 0x43800000, v248
	s_cbranch_vccnz .Lbm3_Ag0_redo
	v_add_f32_e32 v194, v194, v248
	s_waitcnt vmcnt(8)
	s_nop 1
	v_mfma_f32_16x16x32_fp8_fp8 v[100:103], v[36:37], v[84:85], v[100:103]
	v_mfma_f32_16x16x32_fp8_fp8 v[104:107], v[38:39], v[84:85], v[104:107]
	v_mfma_f32_16x16x32_fp8_fp8 v[108:111], v[40:41], v[84:85], v[108:111]
	v_mfma_f32_16x16x32_fp8_fp8 v[112:115], v[42:43], v[84:85], v[112:115]
	v_mfma_f32_16x16x32_fp8_fp8 v[100:103], v[44:45], v[86:87], v[100:103]
	v_mfma_f32_16x16x32_fp8_fp8 v[104:107], v[46:47], v[86:87], v[104:107]
	v_mfma_f32_16x16x32_fp8_fp8 v[108:111], v[48:49], v[86:87], v[108:111]
	v_mfma_f32_16x16x32_fp8_fp8 v[112:115], v[50:51], v[86:87], v[112:115]
	s_branch .Lbm3_Ag0_skip

.Lbm3_Ag0_skip:
	s_bfe_u32 s29, s48, 0x40004
	s_cmp_eq_u32 s29, 0
	s_cbranch_scc1 .Lbm3_Ag1_skip
	s_waitcnt vmcnt(12)
	v_mfma_f32_16x16x32_fp8_fp8 v[84:87], v[2:3], v[168:169], 0
	v_mfma_f32_16x16x32_fp8_fp8 v[88:91], v[6:7], v[168:169], 0
	v_mfma_f32_16x16x32_fp8_fp8 v[92:95], v[12:13], v[168:169], 0
	v_mfma_f32_16x16x32_fp8_fp8 v[96:99], v[16:17], v[168:169], 0
	v_mfma_f32_16x16x32_fp8_fp8 v[84:87], v[4:5], v[170:171], v[84:87]
	v_mfma_f32_16x16x32_fp8_fp8 v[88:91], v[8:9], v[170:171], v[88:91]
	v_mfma_f32_16x16x32_fp8_fp8 v[92:95], v[14:15], v[170:171], v[92:95]
	v_mfma_f32_16x16x32_fp8_fp8 v[96:99], v[18:19], v[170:171], v[96:99]
	v_and_b32_e32 v199, s29, v244
	s_cmp_eq_u32 s50, 1
	v_cmp_ne_u32_e32 vcc, 0, v199
	s_cbranch_scc1 .Lbm3_Ag1_near
	v_add_f32_e32 v200, v81, v191
	v_cndmask_b32_e32 v200, v77, v200, vcc
	v_pk_fma_f32 v[84:85], v[84:85], s[10:11], v[200:201] op_sel_hi:[1,1,0]
	v_pk_fma_f32 v[86:87], v[86:87], s[10:11], v[200:201] op_sel_hi:[1,1,0]
	v_pk_fma_f32 v[88:89], v[88:89], s[10:11], v[200:201] op_sel_hi:[1,1,0]
	v_pk_fma_f32 v[90:91], v[90:91], s[10:11], v[200:201] op_sel_hi:[1,1,0]
	v_pk_fma_f32 v[92:93], v[92:93], s[10:11], v[200:201] op_sel_hi:[1,1,0]
	v_pk_fma_f32 v[94:95], v[94:95], s[10:11], v[200:201] op_sel_hi:[1,1,0]
	v_pk_fma_f32 v[96:97], v[96:97], s[10:11], v[200:201] op_sel_hi:[1,1,0]
	v_pk_fma_f32 v[98:99], v[98:99], s[10:11], v[200:201] op_sel_hi:[1,1,0]
	s_cmp_eq_u32 s35, 0
	s_cbranch_scc1 .Lbm3_Ag1_max
	v_exp_f32_e32 v84, v84
	v_exp_f32_e32 v85, v85
	v_exp_f32_e32 v86, v86
	v_exp_f32_e32 v87, v87
	v_exp_f32_e32 v88, v88
	v_exp_f32_e32 v89, v89
	v_exp_f32_e32 v90, v90
	v_exp_f32_e32 v91, v91
	v_exp_f32_e32 v92, v92
	v_exp_f32_e32 v93, v93
	v_exp_f32_e32 v94, v94
	v_exp_f32_e32 v95, v95
	v_exp_f32_e32 v96, v96
	v_exp_f32_e32 v97, v97
	v_exp_f32_e32 v98, v98
	v_exp_f32_e32 v99, v99
	v_pk_add_f32 v[248:249], v[84:85], v[86:87]
	v_pk_add_f32 v[82:83], v[88:89], v[90:91]
	v_pk_add_f32 v[172:173], v[92:93], v[94:95]
	v_pk_add_f32 v[202:203], v[96:97], v[98:99]
	v_cvt_pk_fp8_f32 v84, v84, v85
	v_cvt_pk_fp8_f32 v85, v88, v89
	v_pk_add_f32 v[248:249], v[248:249], v[82:83]
	v_pk_add_f32 v[172:173], v[172:173], v[202:203]
	v_cvt_pk_fp8_f32 v84, v86, v87 op_sel:[0,0,1]
	v_cvt_pk_fp8_f32 v85, v90, v91 op_sel:[0,0,1]
	v_pk_add_f32 v[248:249], v[248:249], v[172:173]
	v_cvt_pk_fp8_f32 v86, v92, v93
	v_cvt_pk_fp8_f32 v87, v96, v97
	v_add_f32_e32 v248, v248, v249
	v_cvt_pk_fp8_f32 v86, v94, v95 op_sel:[0,0,1]
	v_cvt_pk_fp8_f32 v87, v98, v99 op_sel:[0,0,1]
	v_cmp_lt_f32_e32 vcc, 0x43800000, v248
	s_cbranch_vccnz .Lbm3_Ag1_redo
	v_add_f32_e32 v195, v195, v248
	s_waitcnt vmcnt(8)
	s_nop 1
	v_mfma_f32_16x16x32_fp8_fp8 v[116:119], v[36:37], v[84:85], v[116:119]
	v_mfma_f32_16x16x32_fp8_fp8 v[120:123], v[38:39], v[84:85], v[120:123]
	v_mfma_f32_16x16x32_fp8_fp8 v[124:127], v[40:41], v[84:85], v[124:127]
	v_mfma_f32_16x16x32_fp8_fp8 v[128:131], v[42:43], v[84:85], v[128:131]
	v_mfma_f32_16x16x32_fp8_fp8 v[116:119], v[44:45], v[86:87], v[116:119]
	v_mfma_f32_16x16x32_fp8_fp8 v[120:123], v[46:47], v[86:87], v[120:123]
	v_mfma_f32_16x16x32_fp8_fp8 v[124:127], v[48:49], v[86:87], v[124:127]
	v_mfma_f32_16x16x32_fp8_fp8 v[128:131], v[50:51], v[86:87], v[128:131]
	s_branch .Lbm3_Ag1_skip

.Lbm3_Ag1_skip:
	s_bfe_u32 s29, s48, 0x40008
	s_cmp_eq_u32 s29, 0
	s_cbranch_scc1 .Lbm3_Ag2_skip
	s_waitcnt vmcnt(12)
	v_mfma_f32_16x16x32_fp8_fp8 v[84:87], v[2:3], v[182:183], 0
	v_mfma_f32_16x16x32_fp8_fp8 v[88:91], v[6:7], v[182:183], 0
	v_mfma_f32_16x16x32_fp8_fp8 v[92:95], v[12:13], v[182:183], 0
	v_mfma_f32_16x16x32_fp8_fp8 v[96:99], v[16:17], v[182:183], 0
	v_mfma_f32_16x16x32_fp8_fp8 v[84:87], v[4:5], v[184:185], v[84:87]
	v_mfma_f32_16x16x32_fp8_fp8 v[88:91], v[8:9], v[184:185], v[88:91]
	v_mfma_f32_16x16x32_fp8_fp8 v[92:95], v[14:15], v[184:185], v[92:95]
	v_mfma_f32_16x16x32_fp8_fp8 v[96:99], v[18:19], v[184:185], v[96:99]
	v_and_b32_e32 v199, s29, v244
	s_cmp_eq_u32 s50, 1
	v_cmp_ne_u32_e32 vcc, 0, v199
	s_cbranch_scc1 .Lbm3_Ag2_near
	v_add_f32_e32 v200, v81, v192
	v_cndmask_b32_e32 v200, v77, v200, vcc
	v_pk_fma_f32 v[84:85], v[84:85], s[10:11], v[200:201] op_sel_hi:[1,1,0]
	v_pk_fma_f32 v[86:87], v[86:87], s[10:11], v[200:201] op_sel_hi:[1,1,0]
	v_pk_fma_f32 v[88:89], v[88:89], s[10:11], v[200:201] op_sel_hi:[1,1,0]
	v_pk_fma_f32 v[90:91], v[90:91], s[10:11], v[200:201] op_sel_hi:[1,1,0]
	v_pk_fma_f32 v[92:93], v[92:93], s[10:11], v[200:201] op_sel_hi:[1,1,0]
	v_pk_fma_f32 v[94:95], v[94:95], s[10:11], v[200:201] op_sel_hi:[1,1,0]
	v_pk_fma_f32 v[96:97], v[96:97], s[10:11], v[200:201] op_sel_hi:[1,1,0]
	v_pk_fma_f32 v[98:99], v[98:99], s[10:11], v[200:201] op_sel_hi:[1,1,0]
	s_cmp_eq_u32 s35, 0
	s_cbranch_scc1 .Lbm3_Ag2_max
	v_exp_f32_e32 v84, v84
	v_exp_f32_e32 v85, v85
	v_exp_f32_e32 v86, v86
	v_exp_f32_e32 v87, v87
	v_exp_f32_e32 v88, v88
	v_exp_f32_e32 v89, v89
	v_exp_f32_e32 v90, v90
	v_exp_f32_e32 v91, v91
	v_exp_f32_e32 v92, v92
	v_exp_f32_e32 v93, v93
	v_exp_f32_e32 v94, v94
	v_exp_f32_e32 v95, v95
	v_exp_f32_e32 v96, v96
	v_exp_f32_e32 v97, v97
	v_exp_f32_e32 v98, v98
	v_exp_f32_e32 v99, v99
	v_pk_add_f32 v[248:249], v[84:85], v[86:87]
	v_pk_add_f32 v[82:83], v[88:89], v[90:91]
	v_pk_add_f32 v[172:173], v[92:93], v[94:95]
	v_pk_add_f32 v[202:203], v[96:97], v[98:99]
	v_cvt_pk_fp8_f32 v84, v84, v85
	v_cvt_pk_fp8_f32 v85, v88, v89
	v_pk_add_f32 v[248:249], v[248:249], v[82:83]
	v_pk_add_f32 v[172:173], v[172:173], v[202:203]
	v_cvt_pk_fp8_f32 v84, v86, v87 op_sel:[0,0,1]
	v_cvt_pk_fp8_f32 v85, v90, v91 op_sel:[0,0,1]
	v_pk_add_f32 v[248:249], v[248:249], v[172:173]
	v_cvt_pk_fp8_f32 v86, v92, v93
	v_cvt_pk_fp8_f32 v87, v96, v97
	v_add_f32_e32 v248, v248, v249
	v_cvt_pk_fp8_f32 v86, v94, v95 op_sel:[0,0,1]
	v_cvt_pk_fp8_f32 v87, v98, v99 op_sel:[0,0,1]
	v_cmp_lt_f32_e32 vcc, 0x43800000, v248
	s_cbranch_vccnz .Lbm3_Ag2_redo
	v_add_f32_e32 v196, v196, v248
	s_waitcnt vmcnt(8)
	s_nop 1
	v_mfma_f32_16x16x32_fp8_fp8 v[132:135], v[36:37], v[84:85], v[132:135]
	v_mfma_f32_16x16x32_fp8_fp8 v[136:139], v[38:39], v[84:85], v[136:139]
	v_mfma_f32_16x16x32_fp8_fp8 v[140:143], v[40:41], v[84:85], v[140:143]
	v_mfma_f32_16x16x32_fp8_fp8 v[144:147], v[42:43], v[84:85], v[144:147]
	v_mfma_f32_16x16x32_fp8_fp8 v[132:135], v[44:45], v[86:87], v[132:135]
	v_mfma_f32_16x16x32_fp8_fp8 v[136:139], v[46:47], v[86:87], v[136:139]
	v_mfma_f32_16x16x32_fp8_fp8 v[140:143], v[48:49], v[86:87], v[140:143]
	v_mfma_f32_16x16x32_fp8_fp8 v[144:147], v[50:51], v[86:87], v[144:147]
	s_branch .Lbm3_Ag2_skip

.Lbm3_Ag2_skip:
	s_bfe_u32 s29, s48, 0x4000c
	s_cmp_eq_u32 s29, 0
	s_cbranch_scc1 .Lbm3_Ag3_skip
	s_waitcnt vmcnt(12)
	v_mfma_f32_16x16x32_fp8_fp8 v[84:87], v[2:3], v[186:187], 0
	v_mfma_f32_16x16x32_fp8_fp8 v[88:91], v[6:7], v[186:187], 0
	v_mfma_f32_16x16x32_fp8_fp8 v[92:95], v[12:13], v[186:187], 0
	v_mfma_f32_16x16x32_fp8_fp8 v[96:99], v[16:17], v[186:187], 0
	v_mfma_f32_16x16x32_fp8_fp8 v[84:87], v[4:5], v[188:189], v[84:87]
	v_mfma_f32_16x16x32_fp8_fp8 v[88:91], v[8:9], v[188:189], v[88:91]
	v_mfma_f32_16x16x32_fp8_fp8 v[92:95], v[14:15], v[188:189], v[92:95]
	v_mfma_f32_16x16x32_fp8_fp8 v[96:99], v[18:19], v[188:189], v[96:99]
	v_and_b32_e32 v199, s29, v244
	s_cmp_eq_u32 s50, 1
	v_cmp_ne_u32_e32 vcc, 0, v199
	s_cbranch_scc1 .Lbm3_Ag3_near
	v_add_f32_e32 v200, v81, v193
	v_cndmask_b32_e32 v200, v77, v200, vcc
	v_pk_fma_f32 v[84:85], v[84:85], s[10:11], v[200:201] op_sel_hi:[1,1,0]
	v_pk_fma_f32 v[86:87], v[86:87], s[10:11], v[200:201] op_sel_hi:[1,1,0]
	v_pk_fma_f32 v[88:89], v[88:89], s[10:11], v[200:201] op_sel_hi:[1,1,0]
	v_pk_fma_f32 v[90:91], v[90:91], s[10:11], v[200:201] op_sel_hi:[1,1,0]
	v_pk_fma_f32 v[92:93], v[92:93], s[10:11], v[200:201] op_sel_hi:[1,1,0]
	v_pk_fma_f32 v[94:95], v[94:95], s[10:11], v[200:201] op_sel_hi:[1,1,0]
	v_pk_fma_f32 v[96:97], v[96:97], s[10:11], v[200:201] op_sel_hi:[1,1,0]
	v_pk_fma_f32 v[98:99], v[98:99], s[10:11], v[200:201] op_sel_hi:[1,1,0]
	s_cmp_eq_u32 s35, 0
	s_cbranch_scc1 .Lbm3_Ag3_max
	v_exp_f32_e32 v84, v84
	v_exp_f32_e32 v85, v85
	v_exp_f32_e32 v86, v86
	v_exp_f32_e32 v87, v87
	v_exp_f32_e32 v88, v88
	v_exp_f32_e32 v89, v89
	v_exp_f32_e32 v90, v90
	v_exp_f32_e32 v91, v91
	v_exp_f32_e32 v92, v92
	v_exp_f32_e32 v93, v93
	v_exp_f32_e32 v94, v94
	v_exp_f32_e32 v95, v95
	v_exp_f32_e32 v96, v96
	v_exp_f32_e32 v97, v97
	v_exp_f32_e32 v98, v98
	v_exp_f32_e32 v99, v99
	v_pk_add_f32 v[248:249], v[84:85], v[86:87]
	v_pk_add_f32 v[82:83], v[88:89], v[90:91]
	v_pk_add_f32 v[172:173], v[92:93], v[94:95]
	v_pk_add_f32 v[202:203], v[96:97], v[98:99]
	v_cvt_pk_fp8_f32 v84, v84, v85
	v_cvt_pk_fp8_f32 v85, v88, v89
	v_pk_add_f32 v[248:249], v[248:249], v[82:83]
	v_pk_add_f32 v[172:173], v[172:173], v[202:203]
	v_cvt_pk_fp8_f32 v84, v86, v87 op_sel:[0,0,1]
	v_cvt_pk_fp8_f32 v85, v90, v91 op_sel:[0,0,1]
	v_pk_add_f32 v[248:249], v[248:249], v[172:173]
	v_cvt_pk_fp8_f32 v86, v92, v93
	v_cvt_pk_fp8_f32 v87, v96, v97
	v_add_f32_e32 v248, v248, v249
	v_cvt_pk_fp8_f32 v86, v94, v95 op_sel:[0,0,1]
	v_cvt_pk_fp8_f32 v87, v98, v99 op_sel:[0,0,1]
	v_cmp_lt_f32_e32 vcc, 0x43800000, v248
	s_cbranch_vccnz .Lbm3_Ag3_redo
	v_add_f32_e32 v197, v197, v248
	s_waitcnt vmcnt(8)
	s_nop 1
	v_mfma_f32_16x16x32_fp8_fp8 v[148:151], v[36:37], v[84:85], v[148:151]
	v_mfma_f32_16x16x32_fp8_fp8 v[152:155], v[38:39], v[84:85], v[152:155]
	v_mfma_f32_16x16x32_fp8_fp8 v[156:159], v[40:41], v[84:85], v[156:159]
	v_mfma_f32_16x16x32_fp8_fp8 v[160:163], v[42:43], v[84:85], v[160:163]
	v_mfma_f32_16x16x32_fp8_fp8 v[148:151], v[44:45], v[86:87], v[148:151]
	v_mfma_f32_16x16x32_fp8_fp8 v[152:155], v[46:47], v[86:87], v[152:155]
	v_mfma_f32_16x16x32_fp8_fp8 v[156:159], v[48:49], v[86:87], v[156:159]
	v_mfma_f32_16x16x32_fp8_fp8 v[160:163], v[50:51], v[86:87], v[160:163]
	s_branch .Lbm3_Ag3_skip

.Lbm3_blkB:
	s_lshl_b32 s29, s27, 12
	s_add_u32 s30, s40, s29
	s_addc_u32 s31, s41, 0
	global_load_dwordx4 v[2:5], v79, s[30:31]
	global_load_dwordx4 v[6:9], v79, s[30:31] offset:1024
	global_load_dwordx4 v[12:15], v79, s[30:31] offset:2048
	global_load_dwordx4 v[16:19], v79, s[30:31] offset:3072
	s_lshl_b32 s29, s27, 12
	s_add_u32 s30, s62, s29
	s_addc_u32 s31, s63, 0
	global_load_dwordx4 v[36:39], v79, s[30:31]
	global_load_dwordx4 v[40:43], v79, s[30:31] offset:1024
	global_load_dwordx4 v[44:47], v79, s[30:31] offset:2048
	global_load_dwordx4 v[48:51], v79, s[30:31] offset:3072
	s_add_i32 s50, s35, 2
	s_add_i32 s9, s25, -1
	s_min_i32 s50, s50, s9
	s_lshl_b32 s9, s50, 2
	s_add_i32 s9, s9, s46
	v_mov_b32_e32 v76, s9
	ds_read_b32 v76, v76 offset:16384
	s_cmp_ge_i32 s38, s21
	s_cselect_b32 s50, 1, 0
	s_bfe_u32 s29, s48, 0x40000
	s_cmp_eq_u32 s29, 0
	s_cbranch_scc1 .Lbm3_Bg0_skip
	s_waitcnt vmcnt(12)
	v_mfma_f32_16x16x32_fp8_fp8 v[84:87], v[20:21], v[164:165], 0
	v_mfma_f32_16x16x32_fp8_fp8 v[88:91], v[24:25], v[164:165], 0
	v_mfma_f32_16x16x32_fp8_fp8 v[92:95], v[28:29], v[164:165], 0
	v_mfma_f32_16x16x32_fp8_fp8 v[96:99], v[32:33], v[164:165], 0
	v_mfma_f32_16x16x32_fp8_fp8 v[84:87], v[22:23], v[166:167], v[84:87]
	v_mfma_f32_16x16x32_fp8_fp8 v[88:91], v[26:27], v[166:167], v[88:91]
	v_mfma_f32_16x16x32_fp8_fp8 v[92:95], v[30:31], v[166:167], v[92:95]
	v_mfma_f32_16x16x32_fp8_fp8 v[96:99], v[34:35], v[166:167], v[96:99]
	v_and_b32_e32 v199, s29, v244
	s_cmp_eq_u32 s50, 1
	v_cmp_ne_u32_e32 vcc, 0, v199
	s_cbranch_scc1 .Lbm3_Bg0_near
	v_add_f32_e32 v200, v81, v190
	v_cndmask_b32_e32 v200, v77, v200, vcc
	v_pk_fma_f32 v[84:85], v[84:85], s[10:11], v[200:201] op_sel_hi:[1,1,0]
	v_pk_fma_f32 v[86:87], v[86:87], s[10:11], v[200:201] op_sel_hi:[1,1,0]
	v_pk_fma_f32 v[88:89], v[88:89], s[10:11], v[200:201] op_sel_hi:[1,1,0]
	v_pk_fma_f32 v[90:91], v[90:91], s[10:11], v[200:201] op_sel_hi:[1,1,0]
	v_pk_fma_f32 v[92:93], v[92:93], s[10:11], v[200:201] op_sel_hi:[1,1,0]
	v_pk_fma_f32 v[94:95], v[94:95], s[10:11], v[200:201] op_sel_hi:[1,1,0]
	v_pk_fma_f32 v[96:97], v[96:97], s[10:11], v[200:201] op_sel_hi:[1,1,0]
	v_pk_fma_f32 v[98:99], v[98:99], s[10:11], v[200:201] op_sel_hi:[1,1,0]
	s_cmp_eq_u32 s35, 0
	s_cbranch_scc1 .Lbm3_Bg0_max
	v_exp_f32_e32 v84, v84
	v_exp_f32_e32 v85, v85
	v_exp_f32_e32 v86, v86
	v_exp_f32_e32 v87, v87
	v_exp_f32_e32 v88, v88
	v_exp_f32_e32 v89, v89
	v_exp_f32_e32 v90, v90
	v_exp_f32_e32 v91, v91
	v_exp_f32_e32 v92, v92
	v_exp_f32_e32 v93, v93
	v_exp_f32_e32 v94, v94
	v_exp_f32_e32 v95, v95
	v_exp_f32_e32 v96, v96
	v_exp_f32_e32 v97, v97
	v_exp_f32_e32 v98, v98
	v_exp_f32_e32 v99, v99
	v_pk_add_f32 v[248:249], v[84:85], v[86:87]
	v_pk_add_f32 v[82:83], v[88:89], v[90:91]
	v_pk_add_f32 v[172:173], v[92:93], v[94:95]
	v_pk_add_f32 v[202:203], v[96:97], v[98:99]
	v_cvt_pk_fp8_f32 v84, v84, v85
	v_cvt_pk_fp8_f32 v85, v88, v89
	v_pk_add_f32 v[248:249], v[248:249], v[82:83]
	v_pk_add_f32 v[172:173], v[172:173], v[202:203]
	v_cvt_pk_fp8_f32 v84, v86, v87 op_sel:[0,0,1]
	v_cvt_pk_fp8_f32 v85, v90, v91 op_sel:[0,0,1]
	v_pk_add_f32 v[248:249], v[248:249], v[172:173]
	v_cvt_pk_fp8_f32 v86, v92, v93
	v_cvt_pk_fp8_f32 v87, v96, v97
	v_add_f32_e32 v248, v248, v249
	v_cvt_pk_fp8_f32 v86, v94, v95 op_sel:[0,0,1]
	v_cvt_pk_fp8_f32 v87, v98, v99 op_sel:[0,0,1]
	v_cmp_lt_f32_e32 vcc, 0x43800000, v248
	s_cbranch_vccnz .Lbm3_Bg0_redo
	v_add_f32_e32 v194, v194, v248
	s_waitcnt vmcnt(8)
	s_nop 1
	v_mfma_f32_16x16x32_fp8_fp8 v[100:103], v[52:53], v[84:85], v[100:103]
	v_mfma_f32_16x16x32_fp8_fp8 v[104:107], v[54:55], v[84:85], v[104:107]
	v_mfma_f32_16x16x32_fp8_fp8 v[108:111], v[56:57], v[84:85], v[108:111]
	v_mfma_f32_16x16x32_fp8_fp8 v[112:115], v[58:59], v[84:85], v[112:115]
	v_mfma_f32_16x16x32_fp8_fp8 v[100:103], v[60:61], v[86:87], v[100:103]
	v_mfma_f32_16x16x32_fp8_fp8 v[104:107], v[62:63], v[86:87], v[104:107]
	v_mfma_f32_16x16x32_fp8_fp8 v[108:111], v[64:65], v[86:87], v[108:111]
	v_mfma_f32_16x16x32_fp8_fp8 v[112:115], v[66:67], v[86:87], v[112:115]
	s_branch .Lbm3_Bg0_skip

.Lbm3_Bg0_skip:
	s_bfe_u32 s29, s48, 0x40004
	s_cmp_eq_u32 s29, 0
	s_cbranch_scc1 .Lbm3_Bg1_skip
	s_waitcnt vmcnt(12)
	v_mfma_f32_16x16x32_fp8_fp8 v[84:87], v[20:21], v[168:169], 0
	v_mfma_f32_16x16x32_fp8_fp8 v[88:91], v[24:25], v[168:169], 0
	v_mfma_f32_16x16x32_fp8_fp8 v[92:95], v[28:29], v[168:169], 0
	v_mfma_f32_16x16x32_fp8_fp8 v[96:99], v[32:33], v[168:169], 0
	v_mfma_f32_16x16x32_fp8_fp8 v[84:87], v[22:23], v[170:171], v[84:87]
	v_mfma_f32_16x16x32_fp8_fp8 v[88:91], v[26:27], v[170:171], v[88:91]
	v_mfma_f32_16x16x32_fp8_fp8 v[92:95], v[30:31], v[170:171], v[92:95]
	v_mfma_f32_16x16x32_fp8_fp8 v[96:99], v[34:35], v[170:171], v[96:99]
	v_and_b32_e32 v199, s29, v244
	s_cmp_eq_u32 s50, 1
	v_cmp_ne_u32_e32 vcc, 0, v199
	s_cbranch_scc1 .Lbm3_Bg1_near
	v_add_f32_e32 v200, v81, v191
	v_cndmask_b32_e32 v200, v77, v200, vcc
	v_pk_fma_f32 v[84:85], v[84:85], s[10:11], v[200:201] op_sel_hi:[1,1,0]
	v_pk_fma_f32 v[86:87], v[86:87], s[10:11], v[200:201] op_sel_hi:[1,1,0]
	v_pk_fma_f32 v[88:89], v[88:89], s[10:11], v[200:201] op_sel_hi:[1,1,0]
	v_pk_fma_f32 v[90:91], v[90:91], s[10:11], v[200:201] op_sel_hi:[1,1,0]
	v_pk_fma_f32 v[92:93], v[92:93], s[10:11], v[200:201] op_sel_hi:[1,1,0]
	v_pk_fma_f32 v[94:95], v[94:95], s[10:11], v[200:201] op_sel_hi:[1,1,0]
	v_pk_fma_f32 v[96:97], v[96:97], s[10:11], v[200:201] op_sel_hi:[1,1,0]
	v_pk_fma_f32 v[98:99], v[98:99], s[10:11], v[200:201] op_sel_hi:[1,1,0]
	s_cmp_eq_u32 s35, 0
	s_cbranch_scc1 .Lbm3_Bg1_max
	v_exp_f32_e32 v84, v84
	v_exp_f32_e32 v85, v85
	v_exp_f32_e32 v86, v86
	v_exp_f32_e32 v87, v87
	v_exp_f32_e32 v88, v88
	v_exp_f32_e32 v89, v89
	v_exp_f32_e32 v90, v90
	v_exp_f32_e32 v91, v91
	v_exp_f32_e32 v92, v92
	v_exp_f32_e32 v93, v93
	v_exp_f32_e32 v94, v94
	v_exp_f32_e32 v95, v95
	v_exp_f32_e32 v96, v96
	v_exp_f32_e32 v97, v97
	v_exp_f32_e32 v98, v98
	v_exp_f32_e32 v99, v99
	v_pk_add_f32 v[248:249], v[84:85], v[86:87]
	v_pk_add_f32 v[82:83], v[88:89], v[90:91]
	v_pk_add_f32 v[172:173], v[92:93], v[94:95]
	v_pk_add_f32 v[202:203], v[96:97], v[98:99]
	v_cvt_pk_fp8_f32 v84, v84, v85
	v_cvt_pk_fp8_f32 v85, v88, v89
	v_pk_add_f32 v[248:249], v[248:249], v[82:83]
	v_pk_add_f32 v[172:173], v[172:173], v[202:203]
	v_cvt_pk_fp8_f32 v84, v86, v87 op_sel:[0,0,1]
	v_cvt_pk_fp8_f32 v85, v90, v91 op_sel:[0,0,1]
	v_pk_add_f32 v[248:249], v[248:249], v[172:173]
	v_cvt_pk_fp8_f32 v86, v92, v93
	v_cvt_pk_fp8_f32 v87, v96, v97
	v_add_f32_e32 v248, v248, v249
	v_cvt_pk_fp8_f32 v86, v94, v95 op_sel:[0,0,1]
	v_cvt_pk_fp8_f32 v87, v98, v99 op_sel:[0,0,1]
	v_cmp_lt_f32_e32 vcc, 0x43800000, v248
	s_cbranch_vccnz .Lbm3_Bg1_redo
	v_add_f32_e32 v195, v195, v248
	s_waitcnt vmcnt(8)
	s_nop 1
	v_mfma_f32_16x16x32_fp8_fp8 v[116:119], v[52:53], v[84:85], v[116:119]
	v_mfma_f32_16x16x32_fp8_fp8 v[120:123], v[54:55], v[84:85], v[120:123]
	v_mfma_f32_16x16x32_fp8_fp8 v[124:127], v[56:57], v[84:85], v[124:127]
	v_mfma_f32_16x16x32_fp8_fp8 v[128:131], v[58:59], v[84:85], v[128:131]
	v_mfma_f32_16x16x32_fp8_fp8 v[116:119], v[60:61], v[86:87], v[116:119]
	v_mfma_f32_16x16x32_fp8_fp8 v[120:123], v[62:63], v[86:87], v[120:123]
	v_mfma_f32_16x16x32_fp8_fp8 v[124:127], v[64:65], v[86:87], v[124:127]
	v_mfma_f32_16x16x32_fp8_fp8 v[128:131], v[66:67], v[86:87], v[128:131]
	s_branch .Lbm3_Bg1_skip

.Lbm3_Bg1_skip:
	s_bfe_u32 s29, s48, 0x40008
	s_cmp_eq_u32 s29, 0
	s_cbranch_scc1 .Lbm3_Bg2_skip
	s_waitcnt vmcnt(12)
	v_mfma_f32_16x16x32_fp8_fp8 v[84:87], v[20:21], v[182:183], 0
	v_mfma_f32_16x16x32_fp8_fp8 v[88:91], v[24:25], v[182:183], 0
	v_mfma_f32_16x16x32_fp8_fp8 v[92:95], v[28:29], v[182:183], 0
	v_mfma_f32_16x16x32_fp8_fp8 v[96:99], v[32:33], v[182:183], 0
	v_mfma_f32_16x16x32_fp8_fp8 v[84:87], v[22:23], v[184:185], v[84:87]
	v_mfma_f32_16x16x32_fp8_fp8 v[88:91], v[26:27], v[184:185], v[88:91]
	v_mfma_f32_16x16x32_fp8_fp8 v[92:95], v[30:31], v[184:185], v[92:95]
	v_mfma_f32_16x16x32_fp8_fp8 v[96:99], v[34:35], v[184:185], v[96:99]
	v_and_b32_e32 v199, s29, v244
	s_cmp_eq_u32 s50, 1
	v_cmp_ne_u32_e32 vcc, 0, v199
	s_cbranch_scc1 .Lbm3_Bg2_near
	v_add_f32_e32 v200, v81, v192
	v_cndmask_b32_e32 v200, v77, v200, vcc
	v_pk_fma_f32 v[84:85], v[84:85], s[10:11], v[200:201] op_sel_hi:[1,1,0]
	v_pk_fma_f32 v[86:87], v[86:87], s[10:11], v[200:201] op_sel_hi:[1,1,0]
	v_pk_fma_f32 v[88:89], v[88:89], s[10:11], v[200:201] op_sel_hi:[1,1,0]
	v_pk_fma_f32 v[90:91], v[90:91], s[10:11], v[200:201] op_sel_hi:[1,1,0]
	v_pk_fma_f32 v[92:93], v[92:93], s[10:11], v[200:201] op_sel_hi:[1,1,0]
	v_pk_fma_f32 v[94:95], v[94:95], s[10:11], v[200:201] op_sel_hi:[1,1,0]
	v_pk_fma_f32 v[96:97], v[96:97], s[10:11], v[200:201] op_sel_hi:[1,1,0]
	v_pk_fma_f32 v[98:99], v[98:99], s[10:11], v[200:201] op_sel_hi:[1,1,0]
	s_cmp_eq_u32 s35, 0
	s_cbranch_scc1 .Lbm3_Bg2_max
	v_exp_f32_e32 v84, v84
	v_exp_f32_e32 v85, v85
	v_exp_f32_e32 v86, v86
	v_exp_f32_e32 v87, v87
	v_exp_f32_e32 v88, v88
	v_exp_f32_e32 v89, v89
	v_exp_f32_e32 v90, v90
	v_exp_f32_e32 v91, v91
	v_exp_f32_e32 v92, v92
	v_exp_f32_e32 v93, v93
	v_exp_f32_e32 v94, v94
	v_exp_f32_e32 v95, v95
	v_exp_f32_e32 v96, v96
	v_exp_f32_e32 v97, v97
	v_exp_f32_e32 v98, v98
	v_exp_f32_e32 v99, v99
	v_pk_add_f32 v[248:249], v[84:85], v[86:87]
	v_pk_add_f32 v[82:83], v[88:89], v[90:91]
	v_pk_add_f32 v[172:173], v[92:93], v[94:95]
	v_pk_add_f32 v[202:203], v[96:97], v[98:99]
	v_cvt_pk_fp8_f32 v84, v84, v85
	v_cvt_pk_fp8_f32 v85, v88, v89
	v_pk_add_f32 v[248:249], v[248:249], v[82:83]
	v_pk_add_f32 v[172:173], v[172:173], v[202:203]
	v_cvt_pk_fp8_f32 v84, v86, v87 op_sel:[0,0,1]
	v_cvt_pk_fp8_f32 v85, v90, v91 op_sel:[0,0,1]
	v_pk_add_f32 v[248:249], v[248:249], v[172:173]
	v_cvt_pk_fp8_f32 v86, v92, v93
	v_cvt_pk_fp8_f32 v87, v96, v97
	v_add_f32_e32 v248, v248, v249
	v_cvt_pk_fp8_f32 v86, v94, v95 op_sel:[0,0,1]
	v_cvt_pk_fp8_f32 v87, v98, v99 op_sel:[0,0,1]
	v_cmp_lt_f32_e32 vcc, 0x43800000, v248
	s_cbranch_vccnz .Lbm3_Bg2_redo
	v_add_f32_e32 v196, v196, v248
	s_waitcnt vmcnt(8)
	s_nop 1
	v_mfma_f32_16x16x32_fp8_fp8 v[132:135], v[52:53], v[84:85], v[132:135]
	v_mfma_f32_16x16x32_fp8_fp8 v[136:139], v[54:55], v[84:85], v[136:139]
	v_mfma_f32_16x16x32_fp8_fp8 v[140:143], v[56:57], v[84:85], v[140:143]
	v_mfma_f32_16x16x32_fp8_fp8 v[144:147], v[58:59], v[84:85], v[144:147]
	v_mfma_f32_16x16x32_fp8_fp8 v[132:135], v[60:61], v[86:87], v[132:135]
	v_mfma_f32_16x16x32_fp8_fp8 v[136:139], v[62:63], v[86:87], v[136:139]
	v_mfma_f32_16x16x32_fp8_fp8 v[140:143], v[64:65], v[86:87], v[140:143]
	v_mfma_f32_16x16x32_fp8_fp8 v[144:147], v[66:67], v[86:87], v[144:147]
	s_branch .Lbm3_Bg2_skip

.Lbm3_Bg2_skip:
	s_bfe_u32 s29, s48, 0x4000c
	s_cmp_eq_u32 s29, 0
	s_cbranch_scc1 .Lbm3_Bg3_skip
	s_waitcnt vmcnt(12)
	v_mfma_f32_16x16x32_fp8_fp8 v[84:87], v[20:21], v[186:187], 0
	v_mfma_f32_16x16x32_fp8_fp8 v[88:91], v[24:25], v[186:187], 0
	v_mfma_f32_16x16x32_fp8_fp8 v[92:95], v[28:29], v[186:187], 0
	v_mfma_f32_16x16x32_fp8_fp8 v[96:99], v[32:33], v[186:187], 0
	v_mfma_f32_16x16x32_fp8_fp8 v[84:87], v[22:23], v[188:189], v[84:87]
	v_mfma_f32_16x16x32_fp8_fp8 v[88:91], v[26:27], v[188:189], v[88:91]
	v_mfma_f32_16x16x32_fp8_fp8 v[92:95], v[30:31], v[188:189], v[92:95]
	v_mfma_f32_16x16x32_fp8_fp8 v[96:99], v[34:35], v[188:189], v[96:99]
	v_and_b32_e32 v199, s29, v244
	s_cmp_eq_u32 s50, 1
	v_cmp_ne_u32_e32 vcc, 0, v199
	s_cbranch_scc1 .Lbm3_Bg3_near
	v_add_f32_e32 v200, v81, v193
	v_cndmask_b32_e32 v200, v77, v200, vcc
	v_pk_fma_f32 v[84:85], v[84:85], s[10:11], v[200:201] op_sel_hi:[1,1,0]
	v_pk_fma_f32 v[86:87], v[86:87], s[10:11], v[200:201] op_sel_hi:[1,1,0]
	v_pk_fma_f32 v[88:89], v[88:89], s[10:11], v[200:201] op_sel_hi:[1,1,0]
	v_pk_fma_f32 v[90:91], v[90:91], s[10:11], v[200:201] op_sel_hi:[1,1,0]
	v_pk_fma_f32 v[92:93], v[92:93], s[10:11], v[200:201] op_sel_hi:[1,1,0]
	v_pk_fma_f32 v[94:95], v[94:95], s[10:11], v[200:201] op_sel_hi:[1,1,0]
	v_pk_fma_f32 v[96:97], v[96:97], s[10:11], v[200:201] op_sel_hi:[1,1,0]
	v_pk_fma_f32 v[98:99], v[98:99], s[10:11], v[200:201] op_sel_hi:[1,1,0]
	s_cmp_eq_u32 s35, 0
	s_cbranch_scc1 .Lbm3_Bg3_max
	v_exp_f32_e32 v84, v84
	v_exp_f32_e32 v85, v85
	v_exp_f32_e32 v86, v86
	v_exp_f32_e32 v87, v87
	v_exp_f32_e32 v88, v88
	v_exp_f32_e32 v89, v89
	v_exp_f32_e32 v90, v90
	v_exp_f32_e32 v91, v91
	v_exp_f32_e32 v92, v92
	v_exp_f32_e32 v93, v93
	v_exp_f32_e32 v94, v94
	v_exp_f32_e32 v95, v95
	v_exp_f32_e32 v96, v96
	v_exp_f32_e32 v97, v97
	v_exp_f32_e32 v98, v98
	v_exp_f32_e32 v99, v99
	v_pk_add_f32 v[248:249], v[84:85], v[86:87]
	v_pk_add_f32 v[82:83], v[88:89], v[90:91]
	v_pk_add_f32 v[172:173], v[92:93], v[94:95]
	v_pk_add_f32 v[202:203], v[96:97], v[98:99]
	v_cvt_pk_fp8_f32 v84, v84, v85
	v_cvt_pk_fp8_f32 v85, v88, v89
	v_pk_add_f32 v[248:249], v[248:249], v[82:83]
	v_pk_add_f32 v[172:173], v[172:173], v[202:203]
	v_cvt_pk_fp8_f32 v84, v86, v87 op_sel:[0,0,1]
	v_cvt_pk_fp8_f32 v85, v90, v91 op_sel:[0,0,1]
	v_pk_add_f32 v[248:249], v[248:249], v[172:173]
	v_cvt_pk_fp8_f32 v86, v92, v93
	v_cvt_pk_fp8_f32 v87, v96, v97
	v_add_f32_e32 v248, v248, v249
	v_cvt_pk_fp8_f32 v86, v94, v95 op_sel:[0,0,1]
	v_cvt_pk_fp8_f32 v87, v98, v99 op_sel:[0,0,1]
	v_cmp_lt_f32_e32 vcc, 0x43800000, v248
	s_cbranch_vccnz .Lbm3_Bg3_redo
	v_add_f32_e32 v197, v197, v248
	s_waitcnt vmcnt(8)
	s_nop 1
	v_mfma_f32_16x16x32_fp8_fp8 v[148:151], v[52:53], v[84:85], v[148:151]
	v_mfma_f32_16x16x32_fp8_fp8 v[152:155], v[54:55], v[84:85], v[152:155]
	v_mfma_f32_16x16x32_fp8_fp8 v[156:159], v[56:57], v[84:85], v[156:159]
	v_mfma_f32_16x16x32_fp8_fp8 v[160:163], v[58:59], v[84:85], v[160:163]
	v_mfma_f32_16x16x32_fp8_fp8 v[148:151], v[60:61], v[86:87], v[148:151]
	v_mfma_f32_16x16x32_fp8_fp8 v[152:155], v[62:63], v[86:87], v[152:155]
	v_mfma_f32_16x16x32_fp8_fp8 v[156:159], v[64:65], v[86:87], v[156:159]
	v_mfma_f32_16x16x32_fp8_fp8 v[160:163], v[66:67], v[86:87], v[160:163]
	s_branch .Lbm3_Bg3_skip
